# EpiResid + attention softmax: ds_bpermute cross-lane reductions replaced by v_permlane16/32_swap; K-loop saddr LDS-DMA; EpiVT store-wait fix
# baseline (speedup 1.0000x reference)
.LBB0_971:
	ds_read_b128 v[54:57], v211
	ds_read_b128 v[58:61], v211 offset:64
	v_cmp_gt_i32_e32 vcc, v93, v168
	s_and_b64 vcc, s[6:7], vcc
	v_add_u32_e32 v210, 0x900, v211
	v_ashrrev_i32_e32 v81, 31, v80
	s_waitcnt lgkmcnt(1)
	v_mfma_f32_16x16x32_bf16 v[54:57], v[54:57], v[50:53], 0
	ds_read_b128 v[224:227], v211 offset:16192
	s_waitcnt lgkmcnt(1)
	v_mfma_f32_16x16x32_bf16 v[212:215], v[58:61], v[46:49], v[54:57]
	ds_read_b128 v[58:61], v211 offset:2368
	s_nop 3
	ds_read_b128 v[54:57], v211 offset:2304
	s_waitcnt lgkmcnt(0)
	v_mfma_f32_16x16x32_bf16 v[54:57], v[54:57], v[50:53], 0
	v_mfma_f32_16x16x32_bf16 v[216:219], v[58:61], v[46:49], v[54:57]
	ds_read_b128 v[58:61], v211 offset:4672
	s_nop 5
	ds_read_b128 v[54:57], v211 offset:4608
	s_waitcnt lgkmcnt(0)
	v_mfma_f32_16x16x32_bf16 v[54:57], v[54:57], v[50:53], 0
	v_mfma_f32_16x16x32_bf16 v[220:223], v[58:61], v[46:49], v[54:57]
	ds_read_b128 v[58:61], v211 offset:6976
	s_nop 5
	ds_read_b128 v[54:57], v211 offset:6912
	s_waitcnt lgkmcnt(0)
	v_mfma_f32_16x16x32_bf16 v[54:57], v[54:57], v[50:53], 0
	v_mfma_f32_16x16x32_bf16 v[70:73], v[58:61], v[46:49], v[54:57]
	ds_read_b128 v[58:61], v211 offset:9280
	s_nop 5
	ds_read_b128 v[54:57], v211 offset:9216
	s_waitcnt lgkmcnt(0)
	v_mfma_f32_16x16x32_bf16 v[54:57], v[54:57], v[50:53], 0
	v_fma_f32 v70, v70, s82, -v182
	v_fma_f32 v71, v71, s82, -v183
	v_fma_f32 v72, v72, s82, -v188
	v_mfma_f32_16x16x32_bf16 v[66:69], v[58:61], v[46:49], v[54:57]
	ds_read_b128 v[58:61], v211 offset:11584
	v_fma_f32 v73, v73, s82, -v189
	s_nop 1
	ds_read_b128 v[54:57], v211 offset:11520
	s_waitcnt lgkmcnt(0)
	v_mfma_f32_16x16x32_bf16 v[54:57], v[54:57], v[50:53], 0
	s_nop 0
	v_fma_f32 v66, v66, s82, -v190
	v_fma_f32 v67, v67, s82, -v191
	v_fma_f32 v68, v68, s82, -v192
	v_mfma_f32_16x16x32_bf16 v[62:65], v[58:61], v[46:49], v[54:57]
	ds_read_b128 v[58:61], v211 offset:13888
	v_fma_f32 v69, v69, s82, -v193
	s_nop 0
	ds_read_b128 v[54:57], v211 offset:13824
	s_waitcnt lgkmcnt(0)
	v_mfma_f32_16x16x32_bf16 v[54:57], v[54:57], v[50:53], 0
	s_nop 1
	v_fma_f32 v62, v62, s82, -v194
	v_fma_f32 v63, v63, s82, -v195
	v_fma_f32 v64, v64, s82, -v196
	v_mfma_f32_16x16x32_bf16 v[58:61], v[58:61], v[46:49], v[54:57]
	v_fma_f32 v65, v65, s82, -v197
	s_nop 1
	ds_read_b128 v[54:57], v211 offset:16128
	s_waitcnt lgkmcnt(0)
	v_mfma_f32_16x16x32_bf16 v[54:57], v[54:57], v[50:53], 0
	s_nop 1
	v_fma_f32 v58, v58, s82, -v198
	v_fma_f32 v59, v59, s82, -v199
	v_fma_f32 v60, v60, s82, -v200
	v_mfma_f32_16x16x32_bf16 v[54:57], v[224:227], v[46:49], v[54:57]
	ds_read_b128 v[224:227], v211 offset:18432
	v_fma_f32 v61, v61, s82, -v201
	s_waitcnt lgkmcnt(0)
	v_mfma_f32_16x16x32_bf16 v[50:53], v[224:227], v[50:53], 0
	ds_read_b128 v[224:227], v211 offset:18496
	v_fma_f32 v211, v215, s82, -v173
	v_fma_f32 v215, v219, s82, -v177
	s_waitcnt lgkmcnt(0)
	v_mfma_f32_16x16x32_bf16 v[46:49], v[224:227], v[46:49], v[50:53]
	s_nop 2
	v_fma_f32 v50, v212, s82, -v170
	v_cndmask_b32_e32 v50, v243, v50, vcc
	v_cmp_ge_i32_e32 vcc, v93, v168
	s_and_b64 vcc, s[8:9], vcc
	v_fma_f32 v51, v213, s82, -v171
	v_cndmask_b32_e32 v51, v243, v51, vcc
	v_cmp_gt_i32_e32 vcc, v100, v168
	s_and_b64 vcc, s[10:11], vcc
	v_fma_f32 v53, v214, s82, -v172
	v_cndmask_b32_e32 v53, v243, v53, vcc
	v_cmp_gt_i32_e32 vcc, v102, v168
	s_and_b64 vcc, s[12:13], vcc
	v_fma_f32 v212, v216, s82, -v174
	v_cndmask_b32_e32 v211, v243, v211, vcc
	v_cmp_gt_i32_e32 vcc, v104, v168
	v_fma_f32 v213, v217, s82, -v175
	v_fma_f32 v214, v218, s82, -v176
	v_cndmask_b32_e32 v212, v243, v212, vcc
	v_cmp_gt_i32_e32 vcc, v106, v168
	v_fma_f32 v216, v220, s82, -v178
	v_fma_f32 v217, v221, s82, -v179
	v_cndmask_b32_e32 v213, v243, v213, vcc
	v_cmp_gt_i32_e32 vcc, v108, v168
	v_fma_f32 v218, v222, s82, -v180
	v_fma_f32 v219, v223, s82, -v181
	v_cndmask_b32_e32 v214, v243, v214, vcc
	v_cmp_gt_i32_e32 vcc, v110, v168
	v_max3_f32 v52, v169, v50, v51
	v_max3_f32 v52, v52, v53, v211
	v_cndmask_b32_e32 v215, v243, v215, vcc
	v_cmp_gt_i32_e32 vcc, v112, v168
	v_max3_f32 v52, v52, v212, v213
	v_max3_f32 v52, v52, v214, v215
	v_cndmask_b32_e32 v216, v243, v216, vcc
	v_cmp_gt_i32_e32 vcc, v114, v168
	v_fma_f32 v54, v54, s82, -v202
	v_fma_f32 v46, v46, s82, -v206
	v_cndmask_b32_e32 v217, v243, v217, vcc
	v_cmp_gt_i32_e32 vcc, v116, v168
	v_max3_f32 v52, v52, v216, v217
	v_fma_f32 v47, v47, s82, -v207
	v_cndmask_b32_e32 v218, v243, v218, vcc
	v_cmp_gt_i32_e32 vcc, v118, v168
	v_fma_f32 v48, v48, s82, -v208
	v_cndmask_b32_e64 v46, v243, v46, s[14:15]
	v_cndmask_b32_e32 v219, v243, v219, vcc
	v_cmp_gt_i32_e32 vcc, v120, v168
	v_max3_f32 v52, v52, v218, v219
	v_cndmask_b32_e64 v224, v243, v47, s[16:17]
	v_cndmask_b32_e32 v70, v243, v70, vcc
	v_cmp_gt_i32_e32 vcc, v122, v168
	v_cndmask_b32_e64 v225, v243, v48, s[18:19]
	v_fma_f32 v48, v49, s82, -v209
	v_cndmask_b32_e32 v71, v243, v71, vcc
	v_cmp_gt_i32_e32 vcc, v124, v168
	v_max3_f32 v52, v52, v70, v71
	v_cndmask_b32_e64 v226, v243, v48, s[20:21]
	v_cndmask_b32_e32 v72, v243, v72, vcc
	v_cmp_gt_i32_e32 vcc, v126, v168
	s_nop 1
	v_cndmask_b32_e32 v73, v243, v73, vcc
	v_cmp_gt_i32_e32 vcc, v128, v168
	v_max3_f32 v52, v52, v72, v73
	s_nop 0
	v_cndmask_b32_e32 v66, v243, v66, vcc
	v_cmp_gt_i32_e32 vcc, v130, v168
	s_nop 1
	v_cndmask_b32_e32 v67, v243, v67, vcc
	v_cmp_gt_i32_e32 vcc, v132, v168
	v_max3_f32 v52, v52, v66, v67
	s_nop 0
	v_cndmask_b32_e32 v68, v243, v68, vcc
	v_cmp_gt_i32_e32 vcc, v134, v168
	s_nop 1
	v_cndmask_b32_e32 v69, v243, v69, vcc
	v_cmp_gt_i32_e32 vcc, v136, v168
	v_max3_f32 v52, v52, v68, v69
	s_nop 0
	v_cndmask_b32_e32 v62, v243, v62, vcc
	v_cmp_gt_i32_e32 vcc, v138, v168
	s_nop 1
	v_cndmask_b32_e32 v63, v243, v63, vcc
	v_cmp_gt_i32_e32 vcc, v140, v168
	v_max3_f32 v52, v52, v62, v63
	s_nop 0
	v_cndmask_b32_e32 v64, v243, v64, vcc
	v_cmp_gt_i32_e32 vcc, v142, v168
	s_nop 1
	v_cndmask_b32_e32 v65, v243, v65, vcc
	v_cmp_gt_i32_e32 vcc, v144, v168
	v_max3_f32 v52, v52, v64, v65
	s_nop 0
	v_cndmask_b32_e32 v58, v243, v58, vcc
	v_cmp_gt_i32_e32 vcc, v146, v168
	s_nop 1
	v_cndmask_b32_e32 v59, v243, v59, vcc
	v_cmp_gt_i32_e32 vcc, v148, v168
	v_max3_f32 v52, v52, v58, v59
	s_nop 0
	v_cndmask_b32_e32 v60, v243, v60, vcc
	v_cmp_gt_i32_e32 vcc, v150, v168
	s_nop 1
	v_cndmask_b32_e32 v61, v243, v61, vcc
	v_cmp_gt_i32_e32 vcc, v152, v168
	v_max3_f32 v52, v52, v60, v61
	s_nop 0
	v_cndmask_b32_e32 v220, v243, v54, vcc
	v_cmp_gt_i32_e32 vcc, v154, v168
	v_fma_f32 v54, v55, s82, -v203
	s_nop 0
	v_cndmask_b32_e32 v221, v243, v54, vcc
	v_cmp_gt_i32_e32 vcc, v156, v168
	v_fma_f32 v54, v56, s82, -v204
	v_max3_f32 v52, v52, v220, v221
	v_cndmask_b32_e32 v222, v243, v54, vcc
	v_cmp_gt_i32_e32 vcc, v158, v168
	v_fma_f32 v54, v57, s82, -v205
	v_add_u32_e32 v168, -16, v168
	v_cndmask_b32_e32 v223, v243, v54, vcc
	v_max3_f32 v52, v52, v222, v223
	v_max3_f32 v47, v52, v46, v224
	v_max3_f32 v47, v47, v225, v226
	v_mov_b32_e32 v48, v47
	s_nop 1
	v_permlane16_swap_b32_e32 v47, v48
	s_waitcnt lgkmcnt(0)
	v_max_f32_e32 v48, v48, v48
	v_max_f32_e32 v47, v47, v48
	v_mov_b32_e32 v48, v47
	s_nop 1
	v_permlane32_swap_b32_e32 v47, v48
	s_waitcnt lgkmcnt(0)
	v_max_f32_e32 v48, v48, v48
	v_max_f32_e32 v227, v47, v48
	v_sub_f32_e32 v47, v50, v227
	v_exp_f32_e32 v228, v47
	v_sub_f32_e32 v48, v51, v227
	v_exp_f32_e32 v229, v48
	v_sub_f32_e32 v48, v53, v227
	v_exp_f32_e32 v230, v48
	v_sub_f32_e32 v48, v211, v227
	v_exp_f32_e32 v211, v48
	v_sub_f32_e32 v48, v212, v227
	v_add_f32_e32 v47, 0, v228
	v_exp_f32_e32 v212, v48
	v_sub_f32_e32 v48, v213, v227
	v_add_f32_e32 v47, v229, v47
	v_exp_f32_e32 v213, v48
	v_sub_f32_e32 v48, v214, v227
	v_add_f32_e32 v47, v230, v47
	v_exp_f32_e32 v214, v48
	v_sub_f32_e32 v48, v215, v227
	v_add_f32_e32 v47, v211, v47
	v_exp_f32_e32 v215, v48
	v_sub_f32_e32 v48, v216, v227
	v_add_f32_e32 v47, v212, v47
	v_exp_f32_e32 v231, v48
	v_sub_f32_e32 v48, v217, v227
	v_add_f32_e32 v47, v213, v47
	v_exp_f32_e32 v232, v48
	v_sub_f32_e32 v48, v218, v227
	v_add_f32_e32 v47, v214, v47
	v_exp_f32_e32 v233, v48
	v_sub_f32_e32 v48, v219, v227
	v_add_f32_e32 v47, v215, v47
	v_exp_f32_e32 v234, v48
	v_sub_f32_e32 v48, v70, v227
	v_add_f32_e32 v47, v231, v47
	v_exp_f32_e32 v235, v48
	v_sub_f32_e32 v48, v71, v227
	v_add_f32_e32 v47, v232, v47
	v_exp_f32_e32 v236, v48
	v_sub_f32_e32 v48, v72, v227
	v_add_f32_e32 v47, v233, v47
	v_exp_f32_e32 v72, v48
	v_sub_f32_e32 v48, v73, v227
	v_add_f32_e32 v47, v234, v47
	v_exp_f32_e32 v73, v48
	v_sub_f32_e32 v48, v66, v227
	v_add_f32_e32 v47, v235, v47
	v_exp_f32_e32 v240, v48
	v_sub_f32_e32 v48, v67, v227
	v_add_f32_e32 v47, v236, v47
	v_exp_f32_e32 v241, v48
	v_sub_f32_e32 v48, v68, v227
	v_add_f32_e32 v47, v72, v47
	v_exp_f32_e32 v244, v48
	v_sub_f32_e32 v48, v69, v227
	v_add_f32_e32 v47, v73, v47
	v_exp_f32_e32 v245, v48
	v_sub_f32_e32 v48, v62, v227
	v_add_f32_e32 v47, v240, v47
	v_exp_f32_e32 v246, v48
	v_sub_f32_e32 v48, v63, v227
	v_add_f32_e32 v47, v241, v47
	v_exp_f32_e32 v247, v48
	v_sub_f32_e32 v48, v64, v227
	v_add_f32_e32 v47, v244, v47
	v_exp_f32_e32 v248, v48
	v_sub_f32_e32 v48, v65, v227
	v_add_f32_e32 v47, v245, v47
	v_exp_f32_e32 v249, v48
	v_sub_f32_e32 v48, v58, v227
	v_add_f32_e32 v47, v246, v47
	v_exp_f32_e32 v51, v48
	v_sub_f32_e32 v48, v59, v227
	v_add_f32_e32 v47, v247, v47
	v_exp_f32_e32 v52, v48
	v_sub_f32_e32 v48, v60, v227
	v_add_f32_e32 v47, v248, v47
	v_exp_f32_e32 v53, v48
	v_sub_f32_e32 v48, v61, v227
	v_add_f32_e32 v47, v249, v47
	v_exp_f32_e32 v54, v48
	v_sub_f32_e32 v48, v220, v227
	v_add_f32_e32 v47, v51, v47
	v_exp_f32_e32 v55, v48
	v_sub_f32_e32 v48, v221, v227
	v_add_f32_e32 v47, v52, v47
	v_exp_f32_e32 v56, v48
	v_sub_f32_e32 v48, v222, v227
	v_add_f32_e32 v47, v53, v47
	v_exp_f32_e32 v57, v48
	v_sub_f32_e32 v48, v223, v227
	v_add_f32_e32 v47, v54, v47
	v_exp_f32_e32 v58, v48
	v_add_f32_e32 v47, v55, v47
	v_add_f32_e32 v47, v56, v47
	v_add_f32_e32 v47, v57, v47
	v_sub_f32_e32 v46, v46, v227
	v_add_f32_e32 v48, v58, v47
	v_exp_f32_e32 v47, v46
	v_sub_f32_e32 v49, v225, v227
	v_exp_f32_e32 v49, v49
	v_sub_f32_e32 v50, v226, v227
	v_add_f32_e32 v46, v47, v48
	v_sub_f32_e32 v48, v224, v227
	v_exp_f32_e32 v48, v48
	v_exp_f32_e32 v50, v50
	v_cvt_pk_bf16_f32 v60, v228, v229
	v_cvt_pk_bf16_f32 v61, v230, v211
	v_add_f32_e32 v46, v48, v46
	v_add_f32_e32 v46, v49, v46
	v_add_f32_e32 v46, v50, v46
	v_mov_b32_e32 v59, v46
	s_nop 1
	v_permlane16_swap_b32_e32 v46, v59
	v_add_u32_e32 v211, s22, v165
	v_cvt_pk_bf16_f32 v62, v212, v213
	v_cvt_pk_bf16_f32 v63, v214, v215
	v_add_u32_e32 v224, 0x9800, v211
	s_waitcnt lgkmcnt(0)
	v_add_f32_e32 v46, v46, v59
	v_mov_b32_e32 v59, v46
	s_nop 1
	v_permlane32_swap_b32_e32 v46, v59
	v_add_u32_e32 v225, 0xb800, v211
	v_add_u32_e32 v226, 0xd800, v211
	ds_read2_b64 v[64:67], v224 offset0:32 offset1:36
	ds_read2_b64 v[68:71], v225 offset0:128 offset1:132
	s_waitcnt lgkmcnt(2)
	v_add_f32_e32 v46, v46, v59
	v_sub_f32_e32 v59, v169, v227
	v_exp_f32_e32 v59, v59
	ds_read2_b64 v[212:215], v226 offset0:224 offset1:228
	s_waitcnt lgkmcnt(2)
	v_mfma_f32_16x16x32_bf16 v[64:67], v[64:67], v[60:63], 0
	v_add_f32_e32 v46, v59, v46
	v_add_u32_e32 v59, 0x10200, v211
	ds_read_b64 v[216:217], v59
	v_add_u32_e32 v59, 0x10220, v211
	ds_read_b64 v[218:219], v59
	s_waitcnt lgkmcnt(3)
	v_mfma_f32_16x16x32_bf16 v[68:71], v[68:71], v[60:63], 0
	v_add_u32_e32 v59, 0x10240, v211
	s_add_i32 s22, s22, 32
	s_cmpk_eq_i32 s22, 0x80
	s_waitcnt lgkmcnt(2)
	v_mfma_f32_16x16x32_bf16 v[212:215], v[212:215], v[60:63], 0
	s_waitcnt lgkmcnt(0)
	v_mfma_f32_16x16x32_bf16 v[60:63], v[216:219], v[60:63], 0
	v_cvt_pk_bf16_f32 v216, v231, v232
	v_cvt_pk_bf16_f32 v217, v233, v234
	v_cvt_pk_bf16_f32 v218, v235, v236
	v_cvt_pk_bf16_f32 v219, v72, v73
	ds_read2_b64 v[220:223], v224 offset0:40 offset1:44
	s_waitcnt lgkmcnt(0)
	v_mfma_f32_16x16x32_bf16 v[64:67], v[220:223], v[216:219], v[64:67]
	ds_read2_b64 v[220:223], v225 offset0:136 offset1:140
	s_waitcnt lgkmcnt(0)
	v_mfma_f32_16x16x32_bf16 v[68:71], v[220:223], v[216:219], v[68:71]
	ds_read2_b64 v[220:223], v226 offset0:232 offset1:236
	s_waitcnt lgkmcnt(0)
	v_mfma_f32_16x16x32_bf16 v[212:215], v[220:223], v[216:219], v[212:215]
	ds_read_b64 v[220:221], v59
	v_add_u32_e32 v59, 0x10260, v211
	ds_read_b64 v[222:223], v59
	s_waitcnt lgkmcnt(0)
	v_mfma_f32_16x16x32_bf16 v[60:63], v[220:223], v[216:219], v[60:63]
	v_cvt_pk_bf16_f32 v216, v240, v241
	v_cvt_pk_bf16_f32 v217, v244, v245
	v_cvt_pk_bf16_f32 v218, v246, v247
	v_cvt_pk_bf16_f32 v219, v248, v249
	ds_read2_b64 v[220:223], v224 offset0:48 offset1:52
	s_waitcnt lgkmcnt(0)
	v_mfma_f32_16x16x32_bf16 v[64:67], v[220:223], v[216:219], v[64:67]
	ds_read2_b64 v[220:223], v225 offset0:144 offset1:148
	v_add_u32_e32 v59, 0x10280, v211
	s_waitcnt lgkmcnt(0)
	v_mfma_f32_16x16x32_bf16 v[68:71], v[220:223], v[216:219], v[68:71]
	ds_read2_b64 v[220:223], v226 offset0:240 offset1:244
	s_waitcnt lgkmcnt(0)
	v_mfma_f32_16x16x32_bf16 v[212:215], v[220:223], v[216:219], v[212:215]
	ds_read_b64 v[220:221], v59
	v_add_u32_e32 v59, 0x102a0, v211
	ds_read_b64 v[222:223], v59
	v_cvt_pk_bf16_f32 v52, v51, v52
	v_cvt_pk_bf16_f32 v53, v53, v54
	v_cvt_pk_bf16_f32 v54, v55, v56
	v_cvt_pk_bf16_f32 v55, v57, v58
	ds_read2_b64 v[56:59], v224 offset0:56 offset1:60
	s_waitcnt lgkmcnt(0)
	v_mfma_f32_16x16x32_bf16 v[56:59], v[56:59], v[52:55], v[64:67]
	s_nop 2
	ds_read2_b64 v[64:67], v225 offset0:152 offset1:156
	v_add_u32_e32 v51, 0x102c0, v211
	s_waitcnt lgkmcnt(0)
	v_mfma_f32_16x16x32_bf16 v[64:67], v[64:67], v[52:55], v[68:71]
	s_nop 2
	ds_read2_b64 v[68:71], v226 offset0:248 offset1:252
	s_waitcnt lgkmcnt(0)
	v_mfma_f32_16x16x32_bf16 v[68:71], v[68:71], v[52:55], v[212:215]
	s_nop 2
	ds_read_b64 v[212:213], v51
	v_add_u32_e32 v51, 0x102e0, v211
	ds_read_b64 v[214:215], v51
	v_mfma_f32_16x16x32_bf16 v[60:63], v[220:223], v[216:219], v[60:63]
	v_cvt_pk_bf16_f32 v48, v47, v48
	v_cvt_pk_bf16_f32 v49, v49, v50
	v_cvt_pk_bf16_f32 v50, v1, v1
	s_waitcnt lgkmcnt(0)
	v_mfma_f32_16x16x32_bf16 v[52:55], v[212:215], v[52:55], v[60:63]
	v_cvt_pk_bf16_f32 v51, v1, v1
	s_nop 5
	ds_read2_b64 v[60:63], v224 offset0:64 offset1:68
	v_add_u32_e32 v47, 0xe000, v211
	s_waitcnt lgkmcnt(0)
	v_mfma_f32_16x16x32_bf16 v[56:59], v[60:63], v[48:51], v[56:59]
	ds_read2_b64 v[60:63], v225 offset0:160 offset1:164
	s_waitcnt lgkmcnt(0)
	v_mfma_f32_16x16x32_bf16 v[60:63], v[60:63], v[48:51], v[64:67]
	s_nop 2
	ds_read2_b64 v[64:67], v47 offset1:4
	v_add_u32_e32 v47, 0x10300, v211
	s_waitcnt lgkmcnt(0)
	v_mfma_f32_16x16x32_bf16 v[64:67], v[64:67], v[48:51], v[68:71]
	s_nop 2
	ds_read_b64 v[68:69], v47
	v_add_u32_e32 v47, 0x10320, v211
	ds_read_b64 v[70:71], v47
	v_div_scale_f32 v47, s[28:29], v46, v46, 1.0
	s_waitcnt lgkmcnt(0)
	v_mfma_f32_16x16x32_bf16 v[48:51], v[68:71], v[48:51], v[52:55]
	s_nop 2
	v_rcp_f32_e32 v52, v47
	s_mov_b64 s[28:29], 0xa000
	v_lshl_add_u64 v[82:83], v[82:83], 0, s[28:29]
	v_mov_b32_e32 v211, v210
	v_fma_f32 v53, -v47, v52, 1.0
	v_fmac_f32_e32 v52, v53, v52
	v_div_scale_f32 v53, vcc, 1.0, v46, 1.0
	v_mul_f32_e32 v54, v53, v52
	v_fma_f32 v55, -v47, v54, v53
	v_fmac_f32_e32 v54, v55, v52
	v_fma_f32 v47, -v47, v54, v53
	v_div_fmas_f32 v47, v47, v52, v54
	v_div_fixup_f32 v70, v47, v46, 1.0
	v_lshlrev_b64 v[46:47], 11, v[80:81]
	v_lshl_add_u64 v[68:69], v[84:85], 0, v[46:47]
	v_mul_f32_e32 v46, v70, v56
	v_mul_f32_e32 v47, v70, v57
	v_cvt_pk_bf16_f32 v52, v46, v47
	v_mul_f32_e32 v46, v70, v58
	v_mul_f32_e32 v47, v70, v59
	v_cvt_pk_bf16_f32 v53, v46, v47
	v_mul_f32_e32 v46, v70, v60
	v_mul_f32_e32 v47, v70, v61
	v_cvt_pk_bf16_f32 v54, v46, v47
	v_mul_f32_e32 v46, v70, v62
	v_mul_f32_e32 v47, v70, v63
	v_cvt_pk_bf16_f32 v55, v46, v47
	v_permlane16_swap_b32_e32 v52, v54
	v_permlane16_swap_b32_e32 v53, v55
	v_mul_f32_e32 v46, v70, v64
	v_mul_f32_e32 v47, v70, v65
	global_store_dwordx4 v[68:69], v[52:55], off
	v_cvt_pk_bf16_f32 v46, v46, v47
	v_mul_f32_e32 v47, v70, v66
	v_mul_f32_e32 v48, v70, v48
	v_mul_f32_e32 v49, v70, v49
	v_mul_f32_e32 v52, v70, v67
	v_cvt_pk_bf16_f32 v47, v47, v52
	v_cvt_pk_bf16_f32 v48, v48, v49
	v_mul_f32_e32 v49, v70, v50
	v_mul_f32_e32 v50, v70, v51
	v_cvt_pk_bf16_f32 v49, v49, v50
	v_permlane16_swap_b32_e32 v46, v48
	v_permlane16_swap_b32_e32 v47, v49
	global_store_dwordx4 v[68:69], v[46:49], off offset:64
	s_waitcnt vmcnt(3)
	v_mov_b64_e32 v[52:53], v[44:45]
	v_add_u32_e32 v80, 16, v80
	s_waitcnt vmcnt(2)
	v_mov_b64_e32 v[48:49], v[40:41]
	v_mov_b64_e32 v[46:47], v[38:39]
	v_mov_b64_e32 v[50:51], v[42:43]
	s_cbranch_scc1 .LBB0_947
